# as previous plus 16-way XOR swizzle of the K tile image in LDS (row & 15 instead of row & 7) for the latent-unit attention path
# speedup vs baseline: 1.0184x; 1.0061x over previous
; __device__ __forceinline__ int v_rd_base(int lane) { return ((lane & 3) << 3) | (((lane >> 2) & 3) << 6) | (((lane >> 4) & 1) << 5) | (((lane >> 5) & 1) << 8); }
; #define TILE_BAR(n) do { asm volatile("s_waitcnt vmcnt(" #n ")" ::: "memory"); __builtin_amdgcn_s_barrier(); asm volatile("" ::: "memory"); } while (0)
; __device__ __forceinline__ void attn_unit(const bf16* __restrict__ Qb, const bf16* __restrict__ Kh, const bf16* __restrict__ Vh, int klat0, int nlt, int kctx0, int NT,
;                                           float lam, float post, const float* __restrict__ subw, bf16* __restrict__ Ob, char* lds) {
;     ...
;   const int tid = tid_l, wid = __builtin_amdgcn_readfirstlane(tid >> 6), lane = tid & 63, r32 = lane & 31, hi = lane >> 5;
;   const int sbr = wid >> 2, wq = wid & 3, sb = sbr * 128;
;   char* K_lds = lds + LDS_KR; char* V_lds = lds + LDS_VR;
;   float* ws = (float*)(lds + LDS_WS) + wid * 64; float* li_l = ws; float* al_l = ws + 32;
;   float m_reg = -1e30f, l_reg = 0; f32x16 o[4] = {}; bf16x8 qr[4];
;   const bf16* Qw = Qb + (long)(wq * 32 + r32) * LDK + sbr * 64 + hi * 8;
; #pragma unroll
;   for (int d0 = 0; d0 < 4; ++d0) qr[d0] = *reinterpret_cast<const bf16x8*>(Qw + d0 * 16);
;   unsigned koff[2], voff[2];
; #pragma unroll
;   for (int q = 0; q < 2; ++q) { const int ch = (q * 8 + wid) * 64 + lane;
;     { const int row = ch >> 4, cpos = ch & 15, csrc = cpos ^ (row & 7); koff[q] = (unsigned)(row * LDK + csrc * 8) * 2u; }
;     { const int pb = ch * 16, sub = pb >> 9, within = (pb & 511) >> 1, kk = (sub >> 2) * 8 + (within >> 5), c = (sub & 3) * 32 + (within & 31);
;       const int k = (kk & ~0xC) | ((kk & 4) << 1) | ((kk & 8) >> 1); voff[q] = (unsigned)(k * LDK + c) * 2u; } }
;   const int vb0 = (int)(uintptr_t)V_lds + v_rd_base(lane);
;   const unsigned ldsw = (unsigned)wid * 1024u;
;   typedef __attribute__((address_space(3))) unsigned lds_u32;
;     ...
;   f32x16 pA0, pA1, pB0, pB1; float mnA, mnB, alA, alB; bf16x8 pa0, pa1, pa2, pa3;
;   DMA_TILE(0); DMA_TILE(1); TILE_BAR(4);
;   DMA_TILE(2);
;   qkt(pA0, pA1, KS(0), qr, r32, hi, sb); partialSM(pA0, pA1, m_reg, mnA, alA);
;   TILE_BAR(4);
.LBB0_748:
	s_and_b64 vcc, exec, s[0:1]
	s_cbranch_vccz .LBB0_715
	s_ashr_i32 s0, s8, 9
	s_ashr_i32 s1, s0, 31
	s_lshl_b64 s[4:5], s[0:1], 13
	s_lshl_b32 s1, s8, 7
	s_and_b32 s1, s1, 0x1f80
	s_or_b32 s4, s4, s1
	s_lshl_b64 s[6:7], s[4:5], 11
	v_readlane_b32 s1, v249, 48
	s_add_u32 s1, s1, s6
	v_readlane_b32 s6, v249, 49
	s_addc_u32 s7, s6, s7
	s_lshl_b32 s6, s8, 1
	s_and_b32 s6, s6, 0x380
	s_lshl_b32 s16, s6, 1
	s_add_u32 s6, s1, s16
	s_addc_u32 s7, s7, 0
	v_readlane_b32 s1, v251, 17
	s_add_u32 s20, s1, s16
	v_readlane_b32 s1, v251, 18
	s_addc_u32 s21, s1, 0
	v_readlane_b32 s1, v251, 19
	s_add_u32 s22, s1, s16
	v_readlane_b32 s1, v251, 20
	v_mov_b32_e32 v4, v0
	s_addc_u32 s23, s1, 0
	s_lshl_b32 s8, s0, 13
	s_lshl_b32 s26, s0, 8
	v_mov_b32_e32 v141, v147
	v_readfirstlane_b32 s0, v4
	s_ashr_i32 s1, s0, 6
	v_and_b32_e32 v138, 31, v4
	s_and_b32 s19, s1, 3
	v_lshlrev_b32_e32 v2, 11, v138
	s_ashr_i32 s17, s0, 8
	v_lshl_or_b32 v146, s19, 16, v2
	v_lshl_add_u64 v[2:3], s[6:7], 0, v[146:147]
	s_lshl_b32 s6, s17, 6
	s_ashr_i32 s7, s6, 31
	v_bfe_u32 v5, v4, 2, 2
	v_lshrrev_b32_e32 v7, 1, v4
	v_bfe_u32 v139, v4, 5, 1
	s_and_b32 s9, s0, 0xffffffc0
	v_lshl_add_u64 v[2:3], s[6:7], 1, v[2:3]
	v_and_or_b32 v5, v7, 8, v5
	v_mov_b32_e32 v7, s0
	s_movk_i32 s6, 0xffc0
	v_lshlrev_b32_e32 v140, 4, v139
	v_bfi_b32 v7, s6, v7, v4
	s_ashr_i32 s6, s9, 4
	v_and_b32_e32 v58, 63, v4
	v_lshl_add_u64 v[2:3], v[2:3], 0, v[140:141]
	s_and_b32 s7, s6, 0x1ffff0
	s_lshr_b32 s6, s6, 1
	s_lshl_b32 s10, s9, 2
	global_load_dwordx4 v[126:129], v[2:3], off
	global_load_dwordx4 v[122:125], v[2:3], off offset:32
	global_load_dwordx4 v[118:121], v[2:3], off offset:64
	global_load_dwordx4 v[114:117], v[2:3], off offset:96
	v_and_b32_e32 v2, 15, v4
	v_lshlrev_b32_e32 v3, 3, v58
	v_ashrrev_i32_e32 v8, 4, v7
	s_and_b32 s6, s6, 4
	s_add_i32 s18, s10, 0
	v_and_b32_e32 v6, 24, v3
	v_bitop3_b32 v9, v8, v2, 15 bitop3:0x6c
	v_lshlrev_b32_e32 v8, 11, v8
	s_movk_i32 s10, 0x60
	s_or_b32 s6, s7, s6
	s_addk_i32 s9, 0x200
	v_lshl_or_b32 v146, v9, 4, v8
	v_and_or_b32 v7, v7, s10, v6
	v_or_b32_e32 v8, s6, v5
	s_ashr_i32 s6, s9, 4
	v_lshlrev_b32_e32 v7, 1, v7
	s_and_b32 s7, s6, 0x1ffff0
	s_lshr_b32 s6, s6, 1
	v_lshl_or_b32 v142, v8, 11, v7
	v_or_b32_e32 v7, s9, v58
	s_and_b32 s6, s6, 4
	v_ashrrev_i32_e32 v8, 4, v7
	s_or_b32 s6, s7, s6
	s_ashr_i32 s9, s8, 31
	s_addk_i32 s26, 0x4000
	s_add_i32 s18, s18, 0x1c000
	v_bitop3_b32 v2, v8, v2, 15 bitop3:0x6c
	v_lshlrev_b32_e32 v8, 11, v8
	v_or_b32_e32 v5, s6, v5
	s_lshl_b32 s31, s1, 10
	s_lshl_b64 s[6:7], s[8:9], 11
	v_lshl_or_b32 v144, v2, 4, v8
	v_and_or_b32 v2, v7, s10, v6
	s_add_u32 s10, s20, s6
	s_addc_u32 s11, s21, s7
	s_add_u32 s6, s22, s6
	s_addc_u32 s7, s23, s7
	s_cmp_lg_u32 0, -1
	s_cselect_b32 s1, 0, 0
	s_add_i32 s27, s31, s1
	s_add_i32 s1, s1, 0xc000
	s_add_i32 s36, s31, s1
	s_mov_b32 m0, s27
	v_lshlrev_b32_e32 v2, 1, v2
	global_load_lds_dwordx4 v146, s[10:11]
	s_mov_b32 m0, s36
	v_lshl_or_b32 v154, v5, 11, v2
	global_load_lds_dwordx4 v142, s[6:7]
	s_add_i32 m0, s27, 0x2000
	v_lshlrev_b32_e32 v2, 1, v4
	global_load_lds_dwordx4 v144, s[10:11]
	s_add_i32 m0, s27, 0xe000
	v_and_b32_e32 v2, 32, v2
	global_load_lds_dwordx4 v154, s[6:7]
	s_or_b32 s6, s8, 64
	s_ashr_i32 s7, s6, 31
	s_lshl_b64 s[6:7], s[6:7], 11
	v_lshlrev_b32_e32 v4, 4, v4
	s_add_u32 s10, s20, s6
	v_and_or_b32 v2, v4, s72, v2
	v_and_b32_e32 v3, 0x100, v3
	s_addc_u32 s11, s21, s7
	v_or3_b32 v141, v2, v3, v6
	s_add_u32 s6, s22, s6
	v_add_u32_e32 v164, s1, v141
	s_addc_u32 s7, s23, s7
	s_add_i32 m0, s27, 0x4000
	s_add_i32 s1, s27, 0x10000
	global_load_lds_dwordx4 v146, s[10:11]
	s_mov_b32 m0, s1
	v_lshl_or_b32 v10, s17, 7, v140
	global_load_lds_dwordx4 v142, s[6:7]
	s_add_i32 m0, s27, 0x6000
	v_lshlrev_b32_e32 v11, 8, v138
	global_load_lds_dwordx4 v144, s[10:11]
	s_add_i32 m0, s27, 0x12000
	v_and_b32_e32 v12, 0xf0, v4
	global_load_lds_dwordx4 v154, s[6:7]
	s_or_b32 s6, s8, 0x80
	s_ashr_i32 s7, s6, 31
	s_lshl_b64 s[6:7], s[6:7], 11
	s_add_u32 s10, s20, s6
	s_addc_u32 s11, s21, s7
	s_add_u32 s6, s22, s6
	s_waitcnt vmcnt(4)
	s_barrier
	s_addc_u32 s7, s23, s7
	s_add_i32 m0, s27, 0x8000
	s_add_i32 s1, s27, 0x14000
	global_load_lds_dwordx4 v146, s[10:11]
	s_mov_b32 m0, s1
	v_or_b32_e32 v13, 32, v10
	global_load_lds_dwordx4 v142, s[6:7]
	s_add_i32 m0, s27, 0xa000
	v_xad_u32 v169, v10, v12, v11
	global_load_lds_dwordx4 v144, s[10:11]
	s_add_i32 m0, s27, 0x16000
	v_xad_u32 v170, v13, v12, v11
	global_load_lds_dwordx4 v154, s[6:7]
	v_or_b32_e32 v13, 64, v10
	v_or_b32_e32 v10, 0x60, v10
	v_xad_u32 v171, v13, v12, v11
	v_xad_u32 v172, v10, v12, v11
	v_add_u32_e32 v165, 0, v169
	v_add_u32_e32 v166, 0, v170
	v_add_u32_e32 v167, 0, v171
	v_add_u32_e32 v168, 0, v172
	ds_read_b128 v[2:5], v165
	ds_read_b128 v[6:9], v165 offset:8192
	ds_read_b128 v[34:37], v166
	ds_read_b128 v[38:41], v166 offset:8192
	ds_read_b128 v[42:45], v167
	ds_read_b128 v[46:49], v167 offset:8192
	ds_read_b128 v[50:53], v168
	ds_read_b128 v[54:57], v168 offset:8192
	v_mov_b32_e32 v143, v147
	v_mov_b32_e32 v145, v147
	v_mov_b32_e32 v155, v147
	s_waitcnt lgkmcnt(0)
	s_waitcnt vmcnt(0) lgkmcnt(0)
	v_mfma_f32_32x32x16_bf16 v[18:33], v[2:5], v[126:129], 0
	s_mov_b32 s6, 0x3e38aa3b
	s_waitcnt vmcnt(4)
	s_barrier
; #define TILE_BAR(n) do { asm volatile("s_waitcnt vmcnt(" #n ")" ::: "memory"); __builtin_amdgcn_s_barrier(); asm volatile("" ::: "memory"); } while (0)
; __device__ __forceinline__ void partialSM(f32x16& p0, f32x16& p1, float& m_reg, float& mn, float& alpha) {
;   constexpr float C = SCALE * 1.4426950408889634f;
;   float pmax = p0[0]; for (int r = 1; r < 16; ++r) pmax = fmaxf(pmax, p0[r]); for (int r = 0; r < 16; ++r) pmax = fmaxf(pmax, p1[r]);
;   { auto rr = __builtin_amdgcn_permlane32_swap(__float_as_uint(pmax), __float_as_uint(pmax), false, false);
;     pmax = fmaxf(__uint_as_float(rr[0]), __uint_as_float(rr[1])); }
;   if (__builtin_expect(__all(pmax - m_reg <= THR / SCALE), 1)) { mn = m_reg; alpha = 1.f; }
;   else { mn = fmaxf(m_reg, pmax); alpha = __builtin_amdgcn_exp2f((m_reg - mn) * C); m_reg = mn; }
;   float mnC = -mn * C;
;   for (int r = 0; r < 16; ++r) p0[r] = fmaf(p0[r], C, mnC); for (int r = 0; r < 16; ++r) p1[r] = fmaf(p1[r], C, mnC);
;   for (int r = 0; r < 16; ++r) p0[r] = __builtin_amdgcn_exp2f(p0[r]);
; }
; __device__ __forceinline__ void attn_unit(const bf16* __restrict__ Qb, const bf16* __restrict__ Kh, const bf16* __restrict__ Vh, int klat0, int nlt, int kctx0, int NT,
;                                           float lam, float post, const float* __restrict__ subw, bf16* __restrict__ Ob, char* lds) {
;     ...
;   DMA_TILE(0); DMA_TILE(1); TILE_BAR(4);
;   DMA_TILE(2);
;   qkt(pA0, pA1, KS(0), qr, r32, hi, sb); partialSM(pA0, pA1, m_reg, mnA, alA);
;   TILE_BAR(4);
;   if (sbr == 0) {
;     asm volatile(".p2align 8" ::: "memory");
;     for (int j = 1; j + 1 < NT; j += 2) {
	v_cmp_gt_u32_e64 s[40:41], 32, v58
	v_lshl_add_u32 v162, v138, 2, s18
	v_mfma_f32_32x32x16_bf16 v[18:33], v[34:37], v[122:125], v[18:33]
	v_mfma_f32_32x32x16_bf16 v[2:17], v[6:9], v[126:129], 0
	v_mfma_f32_32x32x16_bf16 v[18:33], v[42:45], v[118:121], v[18:33]
	v_mfma_f32_32x32x16_bf16 v[2:17], v[38:41], v[122:125], v[2:17]
	v_mfma_f32_32x32x16_bf16 v[18:33], v[50:53], v[114:117], v[18:33]
	v_mfma_f32_32x32x16_bf16 v[2:17], v[46:49], v[118:121], v[2:17]
	s_nop 10
	v_max_f32_e32 v34, v19, v19
	v_max_f32_e32 v35, v18, v18
	v_max_f32_e32 v34, v35, v34
	v_max3_f32 v34, v34, v20, v21
	v_max3_f32 v34, v34, v22, v23
	v_max3_f32 v34, v34, v24, v25
	v_max3_f32 v34, v34, v26, v27
	v_mfma_f32_32x32x16_bf16 v[2:17], v[54:57], v[114:117], v[2:17]
	v_max3_f32 v34, v34, v28, v29
	v_max3_f32 v34, v34, v30, v31
	v_max3_f32 v34, v34, v32, v33
	s_nop 8
	v_max3_f32 v34, v34, v2, v3
	v_max3_f32 v34, v34, v4, v5
	v_max3_f32 v34, v34, v6, v7
	v_max3_f32 v34, v34, v8, v9
	v_max3_f32 v34, v34, v10, v11
	v_max3_f32 v34, v34, v12, v13
	v_max3_f32 v34, v34, v14, v15
	v_max3_f32 v34, v34, v16, v17
	v_mov_b32_e32 v35, v34
	s_nop 1
	v_permlane32_swap_b32_e32 v34, v35
	v_max_f32_e32 v35, v35, v35
	v_max_f32_e32 v34, v34, v34
	v_max_f32_e32 v34, v34, v35
	v_add_f32_e32 v35, 0x7149f2ca, v34
	v_max_f32_e32 v34, 0xf149f2ca, v34
	v_cmp_ge_f32_e32 vcc, s63, v35
	v_sub_f32_e32 v35, 0xf149f2ca, v34
	v_mul_f32_e32 v35, 0x3e38aa3b, v35
	v_exp_f32_e32 v35, v35
	s_cmp_eq_u64 vcc, exec
	s_cselect_b64 vcc, -1, 0
	v_cndmask_b32_e32 v174, v34, v248, vcc
	v_mul_f32_e32 v34, 0xbe38aa3b, v174
	v_cndmask_b32_e64 v173, v35, 1.0, vcc
	v_mov_b32_e32 v35, v34
	v_fmamk_f32 v18, v18, 0x3e38aa3b, v34
	v_fmamk_f32 v19, v19, 0x3e38aa3b, v34
	v_fmamk_f32 v20, v20, 0x3e38aa3b, v34
	v_fmamk_f32 v21, v21, 0x3e38aa3b, v34
	v_fmamk_f32 v22, v22, 0x3e38aa3b, v34
	v_fmamk_f32 v23, v23, 0x3e38aa3b, v34
	v_fmamk_f32 v24, v24, 0x3e38aa3b, v34
	v_fmamk_f32 v25, v25, 0x3e38aa3b, v34
	v_fmamk_f32 v26, v26, 0x3e38aa3b, v34
	v_fmamk_f32 v27, v27, 0x3e38aa3b, v34
	v_fmamk_f32 v28, v28, 0x3e38aa3b, v34
	v_fmamk_f32 v29, v29, 0x3e38aa3b, v34
	v_fmamk_f32 v30, v30, 0x3e38aa3b, v34
	v_fmamk_f32 v31, v31, 0x3e38aa3b, v34
	v_fmamk_f32 v32, v32, 0x3e38aa3b, v34
	v_fmac_f32_e32 v35, 0x3e38aa3b, v33
	v_exp_f32_e32 v175, v18
	v_exp_f32_e32 v177, v19
	v_exp_f32_e32 v192, v20
	v_exp_f32_e32 v195, v21
	v_exp_f32_e32 v196, v22
	v_exp_f32_e32 v199, v23
	v_exp_f32_e32 v200, v24
	v_exp_f32_e32 v203, v25
	v_exp_f32_e32 v176, v26
	v_exp_f32_e32 v193, v27
	v_exp_f32_e32 v194, v28
	v_exp_f32_e32 v197, v29
	v_exp_f32_e32 v198, v30
	v_exp_f32_e32 v201, v31
	v_exp_f32_e32 v202, v32
	v_exp_f32_e32 v204, v35
	s_cmpk_lt_u32 s0, 0x100
	v_pk_fma_f32 v[80:81], v[16:17], s[6:7], v[34:35] op_sel_hi:[1,0,0]
	v_pk_fma_f32 v[78:79], v[14:15], s[6:7], v[34:35] op_sel_hi:[1,0,0]
	v_pk_fma_f32 v[76:77], v[12:13], s[6:7], v[34:35] op_sel_hi:[1,0,0]
	v_pk_fma_f32 v[74:75], v[10:11], s[6:7], v[34:35] op_sel_hi:[1,0,0]
	v_pk_fma_f32 v[72:73], v[8:9], s[6:7], v[34:35] op_sel_hi:[1,0,0]
	v_pk_fma_f32 v[70:71], v[6:7], s[6:7], v[34:35] op_sel_hi:[1,0,0]
	v_pk_fma_f32 v[68:69], v[4:5], s[6:7], v[34:35] op_sel_hi:[1,0,0]
	v_pk_fma_f32 v[66:67], v[2:3], s[6:7], v[34:35] op_sel_hi:[1,0,0]
	s_cselect_b64 s[6:7], -1, 0
	s_ashr_i32 s30, s26, 31
	s_cmpk_gt_u32 s0, 0xff
	s_mov_b64 s[0:1], -1
	s_branch .LBB0_768
	.p2align 8
	v_mov_b32_e32 v18, v147
	v_mov_b32_e32 v19, v147
	v_mov_b32_e32 v32, v147
	v_mov_b32_e32 v33, v147
	v_mov_b32_e32 v20, v147
	v_mov_b32_e32 v21, v147
	v_mov_b32_e32 v22, v147
	v_mov_b32_e32 v23, v147
	v_mov_b32_e32 v24, v147
	v_mov_b32_e32 v25, v147
	v_mov_b32_e32 v26, v147
	v_mov_b32_e32 v27, v147
	v_mov_b32_e32 v28, v147
	v_mov_b32_e32 v29, v147
	v_mov_b32_e32 v30, v147
	v_mov_b32_e32 v31, v147
	v_mov_b64_e32 v[64:65], v[32:33]
	v_mov_b64_e32 v[48:49], v[32:33]
	v_mov_b64_e32 v[2:3], v[18:19]
	v_mov_b64_e32 v[106:107], v[80:81]
	v_mov_b32_e32 v163, 0
	s_mov_b32 s12, 1
	s_mov_b32 s37, 0x10000
	v_mov_b64_e32 v[62:63], v[30:31]
	v_mov_b64_e32 v[60:61], v[28:29]
	v_mov_b64_e32 v[58:59], v[26:27]
	v_mov_b64_e32 v[56:57], v[24:25]
	v_mov_b64_e32 v[54:55], v[22:23]
	v_mov_b64_e32 v[52:53], v[20:21]
	v_mov_b64_e32 v[50:51], v[18:19]
	v_mov_b64_e32 v[46:47], v[30:31]
	v_mov_b64_e32 v[44:45], v[28:29]
	v_mov_b64_e32 v[42:43], v[26:27]
	v_mov_b64_e32 v[40:41], v[24:25]
	v_mov_b64_e32 v[38:39], v[22:23]
	v_mov_b64_e32 v[36:37], v[20:21]
	v_mov_b64_e32 v[34:35], v[18:19]
	v_mov_b64_e32 v[4:5], v[20:21]
	v_mov_b64_e32 v[6:7], v[22:23]
	v_mov_b64_e32 v[8:9], v[24:25]
	v_mov_b64_e32 v[10:11], v[26:27]
	v_mov_b64_e32 v[12:13], v[28:29]
	v_mov_b64_e32 v[14:15], v[30:31]
	v_mov_b64_e32 v[16:17], v[32:33]
	v_mov_b32_e32 v207, v173
	v_mov_b64_e32 v[104:105], v[78:79]
	v_mov_b64_e32 v[102:103], v[76:77]
	v_mov_b64_e32 v[100:101], v[74:75]
	v_mov_b64_e32 v[98:99], v[72:73]
	v_mov_b64_e32 v[96:97], v[70:71]
	v_mov_b64_e32 v[94:95], v[68:69]
	v_mov_b64_e32 v[92:93], v[66:67]
	v_mov_b32_e32 v206, v174
	v_mov_b32_e32 v214, v175
	v_mov_b32_e32 v215, v177
	v_mov_b32_e32 v131, v192
	v_mov_b32_e32 v213, v195
	v_mov_b32_e32 v132, v196
	v_mov_b32_e32 v137, v199
	v_mov_b32_e32 v133, v200
	v_mov_b32_e32 v136, v203
	v_mov_b32_e32 v134, v176
	v_mov_b32_e32 v135, v193
	v_mov_b32_e32 v112, v194
	v_mov_b32_e32 v113, v197
	v_mov_b32_e32 v110, v198
	v_mov_b32_e32 v111, v201
	v_mov_b32_e32 v108, v202
	v_mov_b32_e32 v109, v204
